# P4b attention unit: rope(rep0), K(rep1), rope(rep1) and the 4 V-band loads issued up front with counted vmcnt waits instead of 6 serialized load-wait round trips
# baseline (speedup 1.0000x reference)
; __device__ __forceinline__ unsigned pk2(float lo, float hi) { f32x2_t v = {lo, hi}; bf16x2_t b = __builtin_convertvector(v, bf16x2_t); return __builtin_bit_cast(unsigned, b); }
; __device__ __forceinline__ void norm_rope(u32x4 w0, u32x4 w1, const float* __restrict__ gain, int chunk, const float* rp, float scale, float* x) {
;     const unsigned ww[8] = {w0.x, w0.y, w0.z, w0.w, w1.x, w1.y, w1.z, w1.w};
;     float ss = 0.f;
; #pragma unroll
;     for (int i = 0; i < 8; ++i) { x[2 * i] = __uint_as_float(ww[i] << 16); x[2 * i + 1] = __uint_as_float(ww[i] & 0xffff0000u); ss += x[2 * i] * x[2 * i] + x[2 * i + 1] * x[2 * i + 1]; }
; __device__ __forceinline__ void attn_unit(const AtArgs& A, unsigned char* lds, int unit, int tid, int wave, int lane) {
;     ...
;     for (int rep = 0; rep < 2; ++rep) {
;         const int task = tid + rep * 512, key = task >> 2, chunk = task & 3;
;         const int s = (nb - 1) * 128 + key; const bool valid = s >= 0;
;         const size_t t = (size_t)b * SEQ + (valid ? s : 0);
;         float x[16];
;         load_norm_rope(Q + t * QW + QC_K + kvh * 64 + chunk * 16, valid, A.kg, chunk, ROPE + t * 16, 1.0f, x);
;         u32x4 o0, o1; o0.x = pk2(x[0], x[1]); o0.y = pk2(x[2], x[3]); o0.z = pk2(x[4], x[5]); o0.w = pk2(x[6], x[7]); o1.x = pk2(x[8], x[9]); o1.y = pk2(x[10], x[11]); o1.z = pk2(x[12], x[13]); o1.w = pk2(x[14], x[15]);
;         *(u32x4*)(KS + key * KST + chunk * 16) = o0; *(u32x4*)(KS + key * KST + chunk * 16 + 8) = o1;
;     }
; #pragma unroll
;     for (int rep = 0; rep < 4; ++rep) {
;         const int task = tid + rep * 512, key = task >> 3, c8 = task & 7;
;         const int s = (nb - 1) * 128 + key; const bool valid = s >= 0;
;         const size_t t = (size_t)b * SEQ + (valid ? s : 0);
;         u32x4 w = (u32x4){0, 0, 0, 0};
;         if (valid) w = *(const u32x4*)(Q + t * QW + QC_V + kvh * 64 + c8 * 8);
;         const unsigned ww[4] = {w.x, w.y, w.z, w.w};
;         const int pkey = (((key >> 3) ^ c8) << 3) | (key & 7);
; #pragma unroll
;         for (int i = 0; i < 4; ++i) { VT[(c8 * 8 + 2 * i) * VST + pkey] = (bf16)(ww[i] & 0xffffu); VT[(c8 * 8 + 2 * i + 1) * VST + pkey] = (bf16)(ww[i] >> 16); }
;     }
.LBB0_495:
	s_or_b64 exec, exec, s[16:17]
	global_load_dwordx4 v[0:3], v[40:41], off offset:48
	global_load_dwordx4 v[4:7], v[40:41], off offset:32
	global_load_dwordx4 v[16:19], v[40:41], off offset:16
	global_load_dwordx4 v[20:23], v[40:41], off
	s_and_saveexec_b64 s[16:17], s[40:41]
	v_readlane_b32 s12, v241, 15
	v_lshlrev_b64 v[136:137], 6, v[52:53]
	v_readlane_b32 s13, v241, 16
	s_nop 1
	v_lshl_add_u64 v[136:137], s[12:13], 0, v[136:137]
	global_load_dwordx4 v[140:143], v[136:137], off offset:48
	global_load_dwordx4 v[144:147], v[136:137], off offset:16
	global_load_dwordx4 v[148:151], v[136:137], off offset:32
	global_load_dwordx4 v[152:155], v[136:137], off
	s_or_b64 exec, exec, s[16:17]
	v_add_u32_e32 v186, s2, v37
	v_cmp_lt_i32_e32 vcc, -1, v186
	v_mov_b32_e32 v185, v39
	v_mov_b32_e32 v176, 0
	v_cndmask_b32_e32 v184, 0, v186, vcc
	v_lshl_add_u64 v[184:185], s[0:1], 0, v[184:185]
	v_mov_b32_e32 v177, 0
	v_mov_b32_e32 v178, 0
	v_mov_b32_e32 v179, 0
	v_mov_b32_e32 v180, 0
	v_mov_b32_e32 v181, 0
	v_mov_b32_e32 v182, 0
	v_mov_b32_e32 v183, 0
	s_and_saveexec_b64 s[16:17], vcc
	v_mov_b64_e32 v[188:189], s[60:61]
	v_mad_u64_u32 v[188:189], s[12:13], v184, s25, v[188:189]
	v_mad_i32_i24 v189, v185, s25, v189
	s_lshl_b32 s6, s11, 1
	v_lshl_add_u64 v[188:189], v[188:189], 0, s[6:7]
	v_lshl_add_u64 v[188:189], v[188:189], 0, v[38:39]
	global_load_dwordx4 v[176:179], v[188:189], off offset:1024
	global_load_dwordx4 v[180:183], v[188:189], off offset:1040
	s_or_b64 exec, exec, s[16:17]
	s_and_saveexec_b64 s[16:17], s[40:41]
	v_readlane_b32 s12, v241, 15
	v_lshlrev_b64 v[190:191], 6, v[184:185]
	v_readlane_b32 s13, v241, 16
	s_nop 1
	v_lshl_add_u64 v[190:191], s[12:13], 0, v[190:191]
	global_load_dwordx4 v[160:163], v[190:191], off offset:48
	global_load_dwordx4 v[164:167], v[190:191], off offset:16
	global_load_dwordx4 v[168:171], v[190:191], off offset:32
	global_load_dwordx4 v[172:175], v[190:191], off
	s_or_b64 exec, exec, s[16:17]
	v_lshlrev_b32_e32 v206, 1, v42
	v_mov_b32_e32 v207, v39
	v_add_u32_e32 v200, s2, v43
	v_cmp_lt_i32_e32 vcc, -1, v200
	v_mov_b32_e32 v210, 0
	v_mov_b32_e32 v211, 0
	v_mov_b32_e32 v212, 0
	v_mov_b32_e32 v213, 0
	s_and_saveexec_b64 s[16:17], vcc
	v_mov_b32_e32 v201, v39
	v_lshl_add_u64 v[202:203], s[0:1], 0, v[200:201]
	v_mov_b64_e32 v[204:205], s[60:61]
	v_mad_u64_u32 v[204:205], s[12:13], v202, s25, v[204:205]
	v_mad_i32_i24 v205, v203, s25, v205
	s_lshl_b32 s6, s11, 1
	v_lshl_add_u64 v[202:203], v[204:205], 0, s[6:7]
	v_lshl_add_u64 v[202:203], v[202:203], 0, v[206:207]
	global_load_dwordx4 v[210:213], v[202:203], off offset:1280
	s_or_b64 exec, exec, s[16:17]
	v_add_u32_e32 v200, s2, v65
	v_cmp_lt_i32_e32 vcc, -1, v200
	v_mov_b32_e32 v214, 0
	v_mov_b32_e32 v215, 0
	v_mov_b32_e32 v216, 0
	v_mov_b32_e32 v217, 0
	s_and_saveexec_b64 s[16:17], vcc
	v_mov_b32_e32 v201, v39
	v_lshl_add_u64 v[202:203], s[0:1], 0, v[200:201]
	v_mov_b64_e32 v[204:205], s[60:61]
	v_mad_u64_u32 v[204:205], s[12:13], v202, s25, v[204:205]
	v_mad_i32_i24 v205, v203, s25, v205
	s_lshl_b32 s6, s11, 1
	v_lshl_add_u64 v[202:203], v[204:205], 0, s[6:7]
	v_lshl_add_u64 v[202:203], v[202:203], 0, v[206:207]
	global_load_dwordx4 v[214:217], v[202:203], off offset:1280
	s_or_b64 exec, exec, s[16:17]
	v_add_u32_e32 v200, s2, v68
	v_cmp_lt_i32_e32 vcc, -1, v200
	v_mov_b32_e32 v218, 0
	v_mov_b32_e32 v219, 0
	v_mov_b32_e32 v220, 0
	v_mov_b32_e32 v221, 0
	s_and_saveexec_b64 s[16:17], vcc
	v_mov_b32_e32 v201, v39
	v_lshl_add_u64 v[202:203], s[0:1], 0, v[200:201]
	v_mov_b64_e32 v[204:205], s[60:61]
	v_mad_u64_u32 v[204:205], s[12:13], v202, s25, v[204:205]
	v_mad_i32_i24 v205, v203, s25, v205
	s_lshl_b32 s6, s11, 1
	v_lshl_add_u64 v[202:203], v[204:205], 0, s[6:7]
	v_lshl_add_u64 v[202:203], v[202:203], 0, v[206:207]
	global_load_dwordx4 v[218:221], v[202:203], off offset:1280
	s_or_b64 exec, exec, s[16:17]
	v_add_u32_e32 v200, s2, v71
	v_cmp_lt_i32_e32 vcc, -1, v200
	v_mov_b32_e32 v222, 0
	v_mov_b32_e32 v223, 0
	v_mov_b32_e32 v224, 0
	v_mov_b32_e32 v225, 0
	s_and_saveexec_b64 s[16:17], vcc
	v_mov_b32_e32 v201, v39
	v_lshl_add_u64 v[202:203], s[0:1], 0, v[200:201]
	v_mov_b64_e32 v[204:205], s[60:61]
	v_mad_u64_u32 v[204:205], s[12:13], v202, s25, v[204:205]
	v_mad_i32_i24 v205, v203, s25, v205
	s_lshl_b32 s6, s11, 1
	v_lshl_add_u64 v[202:203], v[204:205], 0, s[6:7]
	v_lshl_add_u64 v[202:203], v[202:203], 0, v[206:207]
	global_load_dwordx4 v[222:225], v[202:203], off offset:1280
	s_or_b64 exec, exec, s[16:17]
	s_waitcnt vmcnt(19)
	v_and_b32_e32 v57, 0xffff0000, v31
	v_lshlrev_b32_e32 v56, 16, v31
	v_and_b32_e32 v31, 0xffff0000, v30
	v_lshlrev_b32_e32 v30, 16, v30
	v_mov_b32_e32 v60, v57
	v_mov_b32_e32 v61, v31
	s_waitcnt vmcnt(18)
; __device__ __forceinline__ void rope16(float* x, const float* rp) {
;     const f32x4 c0 = *(const f32x4*)rp, c1 = *(const f32x4*)(rp + 4), s0 = *(const f32x4*)(rp + 8), s1 = *(const f32x4*)(rp + 12);
; #pragma unroll
;     for (int i = 0; i < 8; ++i) {
;         const float cs = (i < 4) ? c0[i & 3] : c1[i & 3], sn = (i < 4) ? s0[i & 3] : s1[i & 3];
;         const float x1 = x[i], x2 = x[8 + i];
;         x[i] = x1 * cs - x2 * sn; x[8 + i] = x2 * cs + x1 * sn;
;     }
; }
; __device__ __forceinline__ void norm_rope(u32x4 w0, u32x4 w1, const float* __restrict__ gain, int chunk, const float* rp, float scale, float* x) {
;     const unsigned ww[8] = {w0.x, w0.y, w0.z, w0.w, w1.x, w1.y, w1.z, w1.w};
;     float ss = 0.f;
; #pragma unroll
;     for (int i = 0; i < 8; ++i) { x[2 * i] = __uint_as_float(ww[i] << 16); x[2 * i + 1] = __uint_as_float(ww[i] & 0xffff0000u); ss += x[2 * i] * x[2 * i] + x[2 * i + 1] * x[2 * i + 1]; }
;     ss += dpp_perm<0xB1, 0xF>(ss); ss += dpp_perm<0x4E, 0xF>(ss);
;     const float inv = rsqrtf(ss * (1.0f / 64.0f) + 1e-6f);
; #pragma unroll
;     for (int i = 0; i < 16; ++i) x[i] = x[i] * inv * gain[chunk * 16 + i];
;     if (chunk == 0) rope16(x, rp);
; #pragma unroll
;     for (int i = 0; i < 16; ++i) x[i] *= scale;
; }
; __device__ __forceinline__ void load_norm_rope(const bf16* p, bool valid, const float* __restrict__ gain, int chunk, const float* rp, float scale, float* x) {
;     u32x4 w0 = (u32x4){0, 0, 0, 0}, w1 = w0;
;     if (valid) { w0 = *(const u32x4*)p; w1 = *(const u32x4*)(p + 8); }
;     norm_rope(w0, w1, gain, chunk, rp, scale, x);
; }
; __device__ __forceinline__ void attn_unit(const AtArgs& A, unsigned char* lds, int unit, int tid, int wave, int lane) {
;     constexpr int KST = 72, VST = 344, PST = 168, QST = 72;
;     bf16* KS = (bf16*)lds;
;     bf16* VT = (bf16*)(lds + 36864);
;     bf16* PS = (bf16*)(lds + 36864 + 44032) + wave * 16 * PST;
;     bf16* QS = (bf16*)(lds + 36864 + 44032 + 8 * 16 * PST * 2) + wave * 16 * QST;
;     const bf16* Q = (const bf16*)(A.ws + WS_QKVG); bf16* YB = (bf16*)(A.ws + WS_YB);
;     const int b = unit >> 6, kvh = (unit >> 5) & 1, nb = unit & 31;
;     const int fr = lane & 15, fq = lane >> 4;
;     const float* ROPE = (const float*)(A.ws + WS_ROPE);
;     u32x4 qn0, qn1;
;     const bf16* pq0;
;     {
	v_and_b32_e32 v55, 0xffff0000, v27
	v_mov_b32_e32 v58, v56
	v_mov_b32_e32 v59, v30
	v_pk_mul_f32 v[60:61], v[60:61], v[60:61]
	v_and_b32_e32 v95, 0xffff0000, v26
	v_lshlrev_b32_e32 v54, 16, v27
	v_pk_fma_f32 v[58:59], v[58:59], v[58:59], v[60:61]
	v_lshlrev_b32_e32 v94, 16, v26
	v_mov_b32_e32 v60, v55
	v_mov_b32_e32 v61, v95
	v_mov_b32_e32 v26, v54
	v_mov_b32_e32 v27, v94
	v_pk_mul_f32 v[60:61], v[60:61], v[60:61]
	v_and_b32_e32 v97, 0xffff0000, v25
	v_pk_fma_f32 v[26:27], v[26:27], v[26:27], v[60:61]
	v_and_b32_e32 v61, 0xffff0000, v29
	v_lshlrev_b32_e32 v60, 16, v29
	v_and_b32_e32 v29, 0xffff0000, v28
	v_lshlrev_b32_e32 v28, 16, v28
	v_mov_b32_e32 v100, v29
	v_mov_b32_e32 v101, v61
	v_mov_b32_e32 v98, v28
	v_mov_b32_e32 v99, v60
	v_pk_mul_f32 v[100:101], v[100:101], v[100:101]
	v_lshlrev_b32_e32 v96, 16, v25
	v_pk_fma_f32 v[98:99], v[98:99], v[98:99], v[100:101]
	v_and_b32_e32 v25, 0xffff0000, v24
	v_lshlrev_b32_e32 v24, 16, v24
	v_mov_b32_e32 v102, v97
	v_mov_b32_e32 v103, v25
	v_add_f32_e32 v98, v98, v99
	v_mov_b32_e32 v100, v96
	v_mov_b32_e32 v101, v24
	v_pk_mul_f32 v[102:103], v[102:103], v[102:103]
	v_add_f32_e32 v59, v59, v98
	v_pk_fma_f32 v[100:101], v[100:101], v[100:101], v[102:103]
	v_add_f32_e32 v58, v58, v59
	v_add_f32_e32 v58, v101, v58
	v_add_f32_e32 v58, v100, v58
	v_add_f32_e32 v27, v27, v58
	v_add_f32_e32 v26, v26, v27
	s_nop 1
	v_add_f32_dpp v26, v26, v26 quad_perm:[1,0,3,2] row_mask:0xf bank_mask:0xf bound_ctrl:1
	s_nop 1
	v_add_f32_dpp v26, v26, v26 quad_perm:[2,3,0,1] row_mask:0xf bank_mask:0xf bound_ctrl:1
	v_fmamk_f32 v26, v26, 0x3c800000, v89
	v_cmp_gt_f32_e32 vcc, s34, v26
	v_mul_f32_e32 v27, 0x4b800000, v26
	s_nop 0
	v_cndmask_b32_e32 v26, v26, v27, vcc
	v_rsq_f32_e32 v26, v26
	s_nop 0
	v_mul_f32_e32 v27, 0x45800000, v26
	v_cndmask_b32_e32 v98, v26, v27, vcc
	v_pk_mul_f32 v[26:27], v[98:99], v[28:29] op_sel_hi:[0,1]
	v_pk_mul_f32 v[28:29], v[98:99], v[60:61] op_sel_hi:[0,1]
	v_pk_mul_f32 v[30:31], v[98:99], v[30:31] op_sel_hi:[0,1]
	v_pk_mul_f32 v[100:101], v[98:99], v[56:57] op_sel_hi:[0,1]
	v_pk_mul_f32 v[24:25], v[98:99], v[24:25] op_sel_hi:[0,1]
	s_waitcnt vmcnt(16)
	v_pk_mul_f32 v[24:25], v[4:5], v[24:25]
	s_waitcnt vmcnt(15)
	v_pk_mul_f32 v[56:57], v[16:17], v[30:31]
	s_waitcnt vmcnt(14)
	v_pk_mul_f32 v[60:61], v[20:21], v[26:27]
	v_pk_mul_f32 v[26:27], v[98:99], v[96:97] op_sel_hi:[0,1]
	v_pk_mul_f32 v[58:59], v[22:23], v[28:29]
	v_pk_mul_f32 v[28:29], v[98:99], v[94:95] op_sel_hi:[0,1]
	v_pk_mul_f32 v[30:31], v[98:99], v[54:55] op_sel_hi:[0,1]
	v_pk_mul_f32 v[26:27], v[6:7], v[26:27]
	v_pk_mul_f32 v[28:29], v[0:1], v[28:29]
	v_pk_mul_f32 v[54:55], v[18:19], v[100:101]
	v_pk_mul_f32 v[30:31], v[2:3], v[30:31]
	s_and_saveexec_b64 s[16:17], s[40:41]
	s_cbranch_execz .LBB0_497
	s_waitcnt vmcnt(11)
	v_pk_mul_f32 v[52:53], v[24:25], v[148:149]
	s_waitcnt vmcnt(10)
	v_pk_fma_f32 v[52:53], v[60:61], v[152:153], v[52:53] neg_lo:[0,0,1] neg_hi:[0,0,1]
	v_pk_mul_f32 v[60:61], v[60:61], v[148:149]
	s_nop 0
	v_pk_fma_f32 v[24:25], v[24:25], v[152:153], v[60:61]
	v_pk_mul_f32 v[60:61], v[26:27], v[150:151]
	s_nop 0
	v_pk_fma_f32 v[60:61], v[58:59], v[154:155], v[60:61] neg_lo:[0,0,1] neg_hi:[0,0,1]
	v_pk_mul_f32 v[58:59], v[58:59], v[150:151]
	s_nop 0
	v_pk_fma_f32 v[26:27], v[26:27], v[154:155], v[58:59]
	v_pk_mul_f32 v[58:59], v[28:29], v[140:141]
	s_nop 0
	v_pk_fma_f32 v[58:59], v[56:57], v[144:145], v[58:59] neg_lo:[0,0,1] neg_hi:[0,0,1]
	v_pk_mul_f32 v[56:57], v[56:57], v[140:141]
	s_nop 0
	v_pk_fma_f32 v[28:29], v[28:29], v[144:145], v[56:57]
	v_pk_mul_f32 v[56:57], v[30:31], v[142:143]
	s_nop 0
	v_pk_fma_f32 v[56:57], v[54:55], v[146:147], v[56:57] neg_lo:[0,0,1] neg_hi:[0,0,1]
	v_pk_mul_f32 v[54:55], v[54:55], v[142:143]
	s_nop 0
	v_pk_fma_f32 v[30:31], v[30:31], v[146:147], v[54:55]
	v_mov_b64_e32 v[54:55], v[56:57]
	v_mov_b64_e32 v[56:57], v[58:59]
	v_mov_b64_e32 v[58:59], v[60:61]
	v_mov_b64_e32 v[60:61], v[52:53]
.LBB0_497:
	s_or_b64 exec, exec, s[16:17]
	v_cvt_pk_bf16_f32 v94, v60, v61
	v_cvt_pk_bf16_f32 v95, v58, v59
	v_cvt_pk_bf16_f32 v96, v56, v57
	v_cvt_pk_bf16_f32 v97, v54, v55
	v_cvt_pk_bf16_f32 v24, v24, v25
	v_cvt_pk_bf16_f32 v25, v26, v27
	v_cvt_pk_bf16_f32 v26, v28, v29
	v_cvt_pk_bf16_f32 v27, v30, v31
	ds_write_b128 v90, v[94:97]
	ds_write_b128 v90, v[24:27] offset:16
	v_mov_b64_e32 v[52:53], v[184:185]
	s_waitcnt vmcnt(8)
	v_mov_b32_e32 v24, v176
	v_mov_b32_e32 v25, v177
	v_mov_b32_e32 v26, v178
	v_mov_b32_e32 v27, v179
	v_mov_b32_e32 v28, v180
	v_mov_b32_e32 v29, v181
	v_mov_b32_e32 v30, v182
	v_mov_b32_e32 v31, v183
; __device__ __forceinline__ void rope16(float* x, const float* rp) {
;     const f32x4 c0 = *(const f32x4*)rp, c1 = *(const f32x4*)(rp + 4), s0 = *(const f32x4*)(rp + 8), s1 = *(const f32x4*)(rp + 12);
; #pragma unroll
;     for (int i = 0; i < 8; ++i) {
;         const float cs = (i < 4) ? c0[i & 3] : c1[i & 3], sn = (i < 4) ? s0[i & 3] : s1[i & 3];
;         const float x1 = x[i], x2 = x[8 + i];
;         x[i] = x1 * cs - x2 * sn; x[8 + i] = x2 * cs + x1 * sn;
;     }
; }
; __device__ __forceinline__ void norm_rope(u32x4 w0, u32x4 w1, const float* __restrict__ gain, int chunk, const float* rp, float scale, float* x) {
;     const unsigned ww[8] = {w0.x, w0.y, w0.z, w0.w, w1.x, w1.y, w1.z, w1.w};
;     float ss = 0.f;
; #pragma unroll
;     for (int i = 0; i < 8; ++i) { x[2 * i] = __uint_as_float(ww[i] << 16); x[2 * i + 1] = __uint_as_float(ww[i] & 0xffff0000u); ss += x[2 * i] * x[2 * i] + x[2 * i + 1] * x[2 * i + 1]; }
;     ss += dpp_perm<0xB1, 0xF>(ss); ss += dpp_perm<0x4E, 0xF>(ss);
;     const float inv = rsqrtf(ss * (1.0f / 64.0f) + 1e-6f);
; #pragma unroll
;     for (int i = 0; i < 16; ++i) x[i] = x[i] * inv * gain[chunk * 16 + i];
;     if (chunk == 0) rope16(x, rp);
; #pragma unroll
;     for (int i = 0; i < 16; ++i) x[i] *= scale;
.LBB0_499:
	s_waitcnt vmcnt(8)
	v_and_b32_e32 v55, 0xffff0000, v27
	v_lshlrev_b32_e32 v54, 16, v27
	v_and_b32_e32 v27, 0xffff0000, v26
	s_waitcnt vmcnt(8)
	v_and_b32_e32 v57, 0xffff0000, v31
	v_lshlrev_b32_e32 v56, 16, v31
	v_lshlrev_b32_e32 v26, 16, v26
	v_mov_b32_e32 v60, v55
	v_mov_b32_e32 v61, v27
	v_and_b32_e32 v31, 0xffff0000, v30
	v_mov_b32_e32 v58, v54
	v_mov_b32_e32 v59, v26
	v_pk_mul_f32 v[60:61], v[60:61], v[60:61]
	v_lshlrev_b32_e32 v30, 16, v30
	v_mov_b32_e32 v94, v57
	v_mov_b32_e32 v95, v31
	v_pk_fma_f32 v[58:59], v[58:59], v[58:59], v[60:61]
	v_mov_b32_e32 v60, v56
	v_mov_b32_e32 v61, v30
	v_pk_mul_f32 v[94:95], v[94:95], v[94:95]
	v_and_b32_e32 v97, 0xffff0000, v29
	v_pk_fma_f32 v[60:61], v[60:61], v[60:61], v[94:95]
	v_and_b32_e32 v95, 0xffff0000, v25
	v_lshlrev_b32_e32 v94, 16, v25
	v_and_b32_e32 v25, 0xffff0000, v24
	v_lshlrev_b32_e32 v24, 16, v24
	v_mov_b32_e32 v100, v25
	v_mov_b32_e32 v101, v95
	v_mov_b32_e32 v98, v24
	v_mov_b32_e32 v99, v94
	v_pk_mul_f32 v[100:101], v[100:101], v[100:101]
	v_lshlrev_b32_e32 v96, 16, v29
	v_pk_fma_f32 v[98:99], v[98:99], v[98:99], v[100:101]
	v_and_b32_e32 v29, 0xffff0000, v28
	v_lshlrev_b32_e32 v28, 16, v28
	v_mov_b32_e32 v102, v97
	v_mov_b32_e32 v103, v29
	v_add_f32_e32 v38, v98, v99
	v_mov_b32_e32 v100, v96
	v_mov_b32_e32 v101, v28
	v_pk_mul_f32 v[102:103], v[102:103], v[102:103]
	v_add_f32_e32 v38, v59, v38
	v_pk_fma_f32 v[100:101], v[100:101], v[100:101], v[102:103]
	v_add_f32_e32 v38, v58, v38
	v_add_f32_e32 v38, v101, v38
	v_add_f32_e32 v38, v100, v38
	v_add_f32_e32 v38, v61, v38
	v_add_f32_e32 v38, v60, v38
	s_nop 1
	v_add_f32_dpp v38, v38, v38 quad_perm:[1,0,3,2] row_mask:0xf bank_mask:0xf bound_ctrl:1
	s_nop 1
	v_add_f32_dpp v38, v38, v38 quad_perm:[2,3,0,1] row_mask:0xf bank_mask:0xf bound_ctrl:1
	v_fmamk_f32 v38, v38, 0x3c800000, v89
	v_mul_f32_e32 v58, 0x4b800000, v38
	v_cmp_gt_f32_e32 vcc, s34, v38
	s_nop 1
	v_cndmask_b32_e32 v38, v38, v58, vcc
	v_rsq_f32_e32 v38, v38
	s_nop 0
	v_mul_f32_e32 v58, 0x45800000, v38
	v_cndmask_b32_e32 v38, v38, v58, vcc
	v_pk_mul_f32 v[24:25], v[38:39], v[24:25] op_sel_hi:[0,1]
	v_pk_mul_f32 v[24:25], v[20:21], v[24:25]
	v_pk_mul_f32 v[20:21], v[38:39], v[94:95] op_sel_hi:[0,1]
	v_pk_mul_f32 v[22:23], v[22:23], v[20:21]
	v_pk_mul_f32 v[20:21], v[38:39], v[26:27] op_sel_hi:[0,1]
	v_pk_mul_f32 v[20:21], v[16:17], v[20:21]
	v_pk_mul_f32 v[16:17], v[38:39], v[54:55] op_sel_hi:[0,1]
	v_pk_mul_f32 v[16:17], v[18:19], v[16:17]
	v_pk_mul_f32 v[18:19], v[38:39], v[28:29] op_sel_hi:[0,1]
	v_pk_mul_f32 v[4:5], v[4:5], v[18:19]
	v_pk_mul_f32 v[18:19], v[38:39], v[96:97] op_sel_hi:[0,1]
	v_pk_mul_f32 v[6:7], v[6:7], v[18:19]
	v_pk_mul_f32 v[18:19], v[38:39], v[30:31] op_sel_hi:[0,1]
	v_pk_mul_f32 v[0:1], v[0:1], v[18:19]
	v_pk_mul_f32 v[18:19], v[38:39], v[56:57] op_sel_hi:[0,1]
	v_pk_mul_f32 v[2:3], v[2:3], v[18:19]
	s_and_saveexec_b64 s[16:17], s[40:41]
	s_cbranch_execz .LBB0_501
	s_waitcnt vmcnt(5)
	v_pk_mul_f32 v[18:19], v[4:5], v[168:169]
	s_waitcnt vmcnt(4)
	v_pk_fma_f32 v[18:19], v[24:25], v[172:173], v[18:19] neg_lo:[0,0,1] neg_hi:[0,0,1]
	v_pk_mul_f32 v[24:25], v[24:25], v[168:169]
	s_nop 0
	v_pk_fma_f32 v[4:5], v[4:5], v[172:173], v[24:25]
	v_pk_mul_f32 v[24:25], v[6:7], v[170:171]
	s_nop 0
	v_pk_fma_f32 v[24:25], v[22:23], v[174:175], v[24:25] neg_lo:[0,0,1] neg_hi:[0,0,1]
	v_pk_mul_f32 v[22:23], v[22:23], v[170:171]
	s_nop 0
	v_pk_fma_f32 v[6:7], v[6:7], v[174:175], v[22:23]
	v_pk_mul_f32 v[22:23], v[0:1], v[160:161]
	s_nop 0
	v_pk_fma_f32 v[22:23], v[20:21], v[164:165], v[22:23] neg_lo:[0,0,1] neg_hi:[0,0,1]
	v_pk_mul_f32 v[20:21], v[20:21], v[160:161]
	s_nop 0
	v_pk_fma_f32 v[0:1], v[0:1], v[164:165], v[20:21]
	v_pk_mul_f32 v[20:21], v[2:3], v[162:163]
	s_nop 0
	v_pk_fma_f32 v[20:21], v[16:17], v[166:167], v[20:21] neg_lo:[0,0,1] neg_hi:[0,0,1]
	v_pk_mul_f32 v[16:17], v[16:17], v[162:163]
	s_nop 0
	v_pk_fma_f32 v[2:3], v[2:3], v[166:167], v[16:17]
	v_mov_b64_e32 v[16:17], v[20:21]
	v_mov_b64_e32 v[20:21], v[22:23]
	v_mov_b64_e32 v[22:23], v[24:25]
	v_mov_b64_e32 v[24:25], v[18:19]
; #define LBAR() do { asm volatile("s_waitcnt lgkmcnt(0)" ::: "memory"); __builtin_amdgcn_s_barrier(); asm volatile("" ::: "memory"); } while (0)
; __device__ __forceinline__ void attn_unit(const AtArgs& A, unsigned char* lds, int unit, int tid, int wave, int lane) {
;     ...
;     for (int rep = 0; rep < 4; ++rep) {
;         const int task = tid + rep * 512, key = task >> 3, c8 = task & 7;
;         const int s = (nb - 1) * 128 + key; const bool valid = s >= 0;
;         const size_t t = (size_t)b * SEQ + (valid ? s : 0);
;         u32x4 w = (u32x4){0, 0, 0, 0};
;         if (valid) w = *(const u32x4*)(Q + t * QW + QC_V + kvh * 64 + c8 * 8);
;         const unsigned ww[4] = {w.x, w.y, w.z, w.w};
;         const int pkey = (((key >> 3) ^ c8) << 3) | (key & 7);
; #pragma unroll
;         for (int i = 0; i < 4; ++i) { VT[(c8 * 8 + 2 * i) * VST + pkey] = (bf16)(ww[i] & 0xffffu); VT[(c8 * 8 + 2 * i + 1) * VST + pkey] = (bf16)(ww[i] >> 16); }
;     }
;     *(u32x4*)(VT + (tid >> 3) * VST + (32 + (tid & 7)) * 8) = (u32x4){0u, 0u, 0u, 0u};
;     LBAR();
;     const int g = wave >> 1, qh = wave & 1, hq = kvh * 4 + g;
;     const float sink = A.sinks[hq];
; #pragma unroll 1
.LBB0_501:
	s_or_b64 exec, exec, s[16:17]
	v_cvt_pk_bf16_f32 v18, v24, v25
	v_cvt_pk_bf16_f32 v19, v22, v23
	v_cvt_pk_bf16_f32 v20, v20, v21
	v_cvt_pk_bf16_f32 v21, v16, v17
	v_cvt_pk_bf16_f32 v4, v4, v5
	v_cvt_pk_bf16_f32 v5, v6, v7
	v_cvt_pk_bf16_f32 v6, v0, v1
	v_add_u32_e32 v38, s2, v43
	v_cvt_pk_bf16_f32 v7, v2, v3
	ds_write_b128 v91, v[18:21]
	ds_write_b128 v91, v[4:7] offset:16
	s_waitcnt vmcnt(0)
	ds_write_b16 v62, v210 offset:36864
	ds_write_b16_d16_hi v63, v210 offset:37552
	ds_write_b16 v62, v211 offset:38240
	ds_write_b16_d16_hi v63, v211 offset:38928
	ds_write_b16 v62, v212 offset:39616
	ds_write_b16_d16_hi v63, v212 offset:40304
	ds_write_b16 v62, v213 offset:40992
	ds_write_b16_d16_hi v63, v213 offset:41680
	ds_write_b16 v66, v214 offset:36864
	ds_write_b16_d16_hi v67, v214 offset:37552
	ds_write_b16 v66, v215 offset:38240
	ds_write_b16_d16_hi v67, v215 offset:38928
	ds_write_b16 v66, v216 offset:39616
	ds_write_b16_d16_hi v67, v216 offset:40304
	ds_write_b16 v66, v217 offset:40992
	ds_write_b16_d16_hi v67, v217 offset:41680
	ds_write_b16 v69, v218 offset:36864
	ds_write_b16_d16_hi v70, v218 offset:37552
	ds_write_b16 v69, v219 offset:38240
	ds_write_b16_d16_hi v70, v219 offset:38928
	ds_write_b16 v69, v220 offset:39616
	ds_write_b16_d16_hi v70, v220 offset:40304
	ds_write_b16 v69, v221 offset:40992
	ds_write_b16_d16_hi v70, v221 offset:41680
	ds_write_b16 v72, v222 offset:36864
	ds_write_b16_d16_hi v73, v222 offset:37552
	ds_write_b16 v72, v223 offset:38240
	ds_write_b16_d16_hi v73, v223 offset:38928
	ds_write_b16 v72, v224 offset:39616
	ds_write_b16_d16_hi v73, v224 offset:40304
	ds_write_b16 v72, v225 offset:40992
	ds_write_b16_d16_hi v73, v225 offset:41680
	s_mov_b32 s2, 0
	ds_write_b128 v74, v[104:107] offset:37376
	s_lshl_b32 s6, s10, 2
	v_readlane_b32 s44, v242, 1
	s_waitcnt lgkmcnt(0)
	s_barrier
	v_mov_b32_e32 v0, s6
	v_readlane_b32 s54, v242, 11
	v_readlane_b32 s55, v242, 12
	s_lshr_b32 s6, s24, 5
	s_and_b32 s6, s6, 1
	s_lshl_b32 s6, s6, 8
	s_and_b32 s12, s35, 31
	s_add_i32 s6, s15, s6
	global_load_dword v38, v0, s[54:55]
	s_lshl_b32 s18, s12, 17
	s_lshl_b64 s[10:11], s[6:7], 1
	s_lshl_b32 s6, s12, 7
	s_cmp_lg_u32 s3, 0
	s_cselect_b64 s[16:17], -1, 0
	s_lshl_b64 s[12:13], s[20:21], 22
	s_or_b32 s3, s12, s18
	s_add_u32 s10, s3, s10
	s_addc_u32 s11, s13, s11
	s_add_u32 s0, s6, s0
	s_addc_u32 s1, 0, s1
	v_lshl_add_u64 v[0:1], s[0:1], 0, v[48:49]
	v_lshlrev_b64 v[0:1], 6, v[0:1]
	v_lshl_add_u64 v[52:53], v[46:47], 0, s[10:11]
	v_lshl_add_u64 v[54:55], s[8:9], 0, v[0:1]
	s_mov_b32 s3, 0xb000
	s_mov_b64 s[20:21], 0
	v_mov_b32_e32 v94, v87
	v_mov_b32_e32 v95, v86
	v_readlane_b32 s45, v242, 2
	v_readlane_b32 s46, v242, 3
	v_readlane_b32 s47, v242, 4
	v_readlane_b32 s48, v242, 5
	v_readlane_b32 s49, v242, 6
	v_readlane_b32 s50, v242, 7
	v_readlane_b32 s51, v242, 8
	v_readlane_b32 s52, v242, 9
	v_readlane_b32 s53, v242, 10
	v_readlane_b32 s56, v242, 13
	v_readlane_b32 s57, v242, 14
	v_readlane_b32 s58, v242, 15
	v_readlane_b32 s59, v242, 16
	s_branch .LBB0_511
